# v41 plus in-projection LN-fold sums fused into the prologue as well; the separate fold weight-reading loop no longer runs
# baseline (speedup 1.0000x reference)
.LBB0_215:
	v_readlane_b32 s0, v254, 30
	s_add_i32 s0, s0, 4
	v_readlane_b32 s90, v255, 16
	v_readlane_b32 s94, v255, 18
	v_readlane_b32 s80, v254, 57
	v_readlane_b32 s84, v254, 59
	s_cmp_lt_u32 s0, 11
	v_readlane_b32 s87, v255, 15
	v_readlane_b32 s91, v255, 17
	v_readlane_b32 s95, v255, 19
	v_readlane_b32 s81, v254, 58
	v_readlane_b32 s85, v254, 60
	v_readlane_b32 s50, v254, 61
	v_readlane_b32 s86, v254, 63
	v_readlane_b32 s88, v255, 5
	v_readlane_b32 s89, v255, 6
	v_readlane_b32 s92, v255, 7
	v_readlane_b32 s93, v255, 8
	v_readlane_b32 s96, v255, 9
	v_readlane_b32 s97, v255, 10
	v_readlane_b32 s51, v254, 62
	s_cbranch_scc0 .LBB0_231
	v_readfirstlane_b32 s0, v223
	s_ashr_i32 s0, s0, 6
	v_readlane_b32 s1, v253, 22
	s_add_i32 s0, s0, s1
	v_readlane_b32 s1, v254, 10
	v_readlane_b32 s4, v252, 0
	s_mov_b32 s5, 0xec00
	s_nop 2
	s_cmpk_eq_u32 s4, 0x100
	s_cselect_b32 s1, 8, s1
	s_cselect_b32 s5, 0, s5
	s_mul_i32 s8, s0, s1
	s_add_i32 s0, s8, s1
	s_min_i32 s4, s0, s5
	s_cmp_ge_i32 s8, s4
	s_cbranch_scc1 .LBB0_231
	v_lshlrev_b32_e32 v0, 3, v135
	v_cmp_eq_u32_e64 s[36:37], 0, v135
	v_lshlrev_b32_e32 v72, 4, v135
	v_mov_b32_e32 v73, v85
	v_lshlrev_b32_e32 v84, 2, v0
	s_branch .LBB0_219

.Lfp_skip:
	s_or_b64 exec, exec, s[4:5]
	s_lshl_b32 s0, s99, 9
	v_add_u32_e32 v0, s0, v223
	s_movk_i32 s0, 0x3c00
	v_cmp_gt_u32_e32 vcc, s0, v0
	s_and_saveexec_b64 s[4:5], vcc
	s_cbranch_execz .Lfp2_skip
	v_mov_b32_e32 v1, 1
	s_movk_i32 s0, 0x1400
	v_cmp_le_u32_e32 vcc, s0, v0
	s_nop 1
	v_addc_co_u32_e32 v1, vcc, 0, v1, vcc
	s_movk_i32 s0, 0x2800
	v_cmp_le_u32_e32 vcc, s0, v0
	s_nop 1
	v_addc_co_u32_e32 v1, vcc, 0, v1, vcc
	v_add_u32_e32 v2, -1, v1
	v_mul_u32_u24_e32 v2, 0x1400, v2
	v_sub_u32_e32 v2, v0, v2
	v_mul_u32_u24_e32 v3, 0x28000, v1
	v_add_lshl_u32 v3, v3, v2, 3
	s_add_u32 s6, s20, 0x1ac00000
	s_addc_u32 s7, s21, 0
	v_mov_b32_e32 v4, s6
	v_mov_b32_e32 v5, s7
	v_add_co_u32_e32 v4, vcc, v3, v4
	s_nop 1
	v_addc_co_u32_e32 v5, vcc, 0, v5, vcc
	global_load_dwordx2 v[10:11], v[4:5], off
	v_add_co_u32_e32 v4, vcc, 0xa000, v4
	s_nop 1
	v_addc_co_u32_e32 v5, vcc, 0, v5, vcc
	global_load_dwordx2 v[12:13], v[4:5], off
	v_add_co_u32_e32 v4, vcc, 0xa000, v4
	s_nop 1
	v_addc_co_u32_e32 v5, vcc, 0, v5, vcc
	global_load_dwordx2 v[14:15], v[4:5], off
	v_add_co_u32_e32 v4, vcc, 0xa000, v4
	s_nop 1
	v_addc_co_u32_e32 v5, vcc, 0, v5, vcc
	global_load_dwordx2 v[16:17], v[4:5], off
	v_add_co_u32_e32 v4, vcc, 0xa000, v4
	s_nop 1
	v_addc_co_u32_e32 v5, vcc, 0, v5, vcc
	global_load_dwordx2 v[18:19], v[4:5], off
	v_add_co_u32_e32 v4, vcc, 0xa000, v4
	s_nop 1
	v_addc_co_u32_e32 v5, vcc, 0, v5, vcc
	global_load_dwordx2 v[20:21], v[4:5], off
	v_add_co_u32_e32 v4, vcc, 0xa000, v4
	s_nop 1
	v_addc_co_u32_e32 v5, vcc, 0, v5, vcc
	global_load_dwordx2 v[22:23], v[4:5], off
	v_add_co_u32_e32 v4, vcc, 0xa000, v4
	s_nop 1
	v_addc_co_u32_e32 v5, vcc, 0, v5, vcc
	global_load_dwordx2 v[24:25], v[4:5], off
	v_add_co_u32_e32 v4, vcc, 0xa000, v4
	s_nop 1
	v_addc_co_u32_e32 v5, vcc, 0, v5, vcc
	global_load_dwordx2 v[26:27], v[4:5], off
	v_add_co_u32_e32 v4, vcc, 0xa000, v4
	s_nop 1
	v_addc_co_u32_e32 v5, vcc, 0, v5, vcc
	global_load_dwordx2 v[28:29], v[4:5], off
	v_add_co_u32_e32 v4, vcc, 0xa000, v4
	s_nop 1
	v_addc_co_u32_e32 v5, vcc, 0, v5, vcc
	global_load_dwordx2 v[30:31], v[4:5], off
	v_add_co_u32_e32 v4, vcc, 0xa000, v4
	s_nop 1
	v_addc_co_u32_e32 v5, vcc, 0, v5, vcc
	global_load_dwordx2 v[32:33], v[4:5], off
	v_add_co_u32_e32 v4, vcc, 0xa000, v4
	s_nop 1
	v_addc_co_u32_e32 v5, vcc, 0, v5, vcc
	global_load_dwordx2 v[34:35], v[4:5], off
	v_add_co_u32_e32 v4, vcc, 0xa000, v4
	s_nop 1
	v_addc_co_u32_e32 v5, vcc, 0, v5, vcc
	global_load_dwordx2 v[36:37], v[4:5], off
	v_add_co_u32_e32 v4, vcc, 0xa000, v4
	s_nop 1
	v_addc_co_u32_e32 v5, vcc, 0, v5, vcc
	global_load_dwordx2 v[38:39], v[4:5], off
	v_add_co_u32_e32 v4, vcc, 0xa000, v4
	s_nop 1
	v_addc_co_u32_e32 v5, vcc, 0, v5, vcc
	global_load_dwordx2 v[40:41], v[4:5], off
	v_add_co_u32_e32 v4, vcc, 0xa000, v4
	s_nop 1
	v_addc_co_u32_e32 v5, vcc, 0, v5, vcc
	global_load_dwordx2 v[42:43], v[4:5], off
	v_add_co_u32_e32 v4, vcc, 0xa000, v4
	s_nop 1
	v_addc_co_u32_e32 v5, vcc, 0, v5, vcc
	global_load_dwordx2 v[44:45], v[4:5], off
	v_add_co_u32_e32 v4, vcc, 0xa000, v4
	s_nop 1
	v_addc_co_u32_e32 v5, vcc, 0, v5, vcc
	global_load_dwordx2 v[46:47], v[4:5], off
	v_add_co_u32_e32 v4, vcc, 0xa000, v4
	s_nop 1
	v_addc_co_u32_e32 v5, vcc, 0, v5, vcc
	global_load_dwordx2 v[48:49], v[4:5], off
	v_add_co_u32_e32 v4, vcc, 0xa000, v4
	s_nop 1
	v_addc_co_u32_e32 v5, vcc, 0, v5, vcc
	global_load_dwordx2 v[50:51], v[4:5], off
	v_add_co_u32_e32 v4, vcc, 0xa000, v4
	s_nop 1
	v_addc_co_u32_e32 v5, vcc, 0, v5, vcc
	global_load_dwordx2 v[52:53], v[4:5], off
	v_add_co_u32_e32 v4, vcc, 0xa000, v4
	s_nop 1
	v_addc_co_u32_e32 v5, vcc, 0, v5, vcc
	global_load_dwordx2 v[54:55], v[4:5], off
	v_add_co_u32_e32 v4, vcc, 0xa000, v4
	s_nop 1
	v_addc_co_u32_e32 v5, vcc, 0, v5, vcc
	global_load_dwordx2 v[56:57], v[4:5], off
	v_add_co_u32_e32 v4, vcc, 0xa000, v4
	s_nop 1
	v_addc_co_u32_e32 v5, vcc, 0, v5, vcc
	global_load_dwordx2 v[58:59], v[4:5], off
	v_add_co_u32_e32 v4, vcc, 0xa000, v4
	s_nop 1
	v_addc_co_u32_e32 v5, vcc, 0, v5, vcc
	global_load_dwordx2 v[60:61], v[4:5], off
	v_add_co_u32_e32 v4, vcc, 0xa000, v4
	s_nop 1
	v_addc_co_u32_e32 v5, vcc, 0, v5, vcc
	global_load_dwordx2 v[62:63], v[4:5], off
	v_add_co_u32_e32 v4, vcc, 0xa000, v4
	s_nop 1
	v_addc_co_u32_e32 v5, vcc, 0, v5, vcc
	global_load_dwordx2 v[64:65], v[4:5], off
	v_add_co_u32_e32 v4, vcc, 0xa000, v4
	s_nop 1
	v_addc_co_u32_e32 v5, vcc, 0, v5, vcc
	global_load_dwordx2 v[66:67], v[4:5], off
	v_add_co_u32_e32 v4, vcc, 0xa000, v4
	s_nop 1
	v_addc_co_u32_e32 v5, vcc, 0, v5, vcc
	global_load_dwordx2 v[68:69], v[4:5], off
	v_add_co_u32_e32 v4, vcc, 0xa000, v4
	s_nop 1
	v_addc_co_u32_e32 v5, vcc, 0, v5, vcc
	global_load_dwordx2 v[70:71], v[4:5], off
	v_add_co_u32_e32 v4, vcc, 0xa000, v4
	s_nop 1
	v_addc_co_u32_e32 v5, vcc, 0, v5, vcc
	global_load_dwordx2 v[72:73], v[4:5], off
	s_waitcnt vmcnt(0)
	v_add_f32_e32 v10, v10, v12
	v_add_f32_e32 v11, v11, v13
	v_add_f32_e32 v10, v10, v14
	v_add_f32_e32 v11, v11, v15
	v_add_f32_e32 v10, v10, v16
	v_add_f32_e32 v11, v11, v17
	v_add_f32_e32 v10, v10, v18
	v_add_f32_e32 v11, v11, v19
	v_add_f32_e32 v10, v10, v20
	v_add_f32_e32 v11, v11, v21
	v_add_f32_e32 v10, v10, v22
	v_add_f32_e32 v11, v11, v23
	v_add_f32_e32 v10, v10, v24
	v_add_f32_e32 v11, v11, v25
	v_add_f32_e32 v10, v10, v26
	v_add_f32_e32 v11, v11, v27
	v_add_f32_e32 v10, v10, v28
	v_add_f32_e32 v11, v11, v29
	v_add_f32_e32 v10, v10, v30
	v_add_f32_e32 v11, v11, v31
	v_add_f32_e32 v10, v10, v32
	v_add_f32_e32 v11, v11, v33
	v_add_f32_e32 v10, v10, v34
	v_add_f32_e32 v11, v11, v35
	v_add_f32_e32 v10, v10, v36
	v_add_f32_e32 v11, v11, v37
	v_add_f32_e32 v10, v10, v38
	v_add_f32_e32 v11, v11, v39
	v_add_f32_e32 v10, v10, v40
	v_add_f32_e32 v11, v11, v41
	v_add_f32_e32 v10, v10, v42
	v_add_f32_e32 v11, v11, v43
	v_add_f32_e32 v10, v10, v44
	v_add_f32_e32 v11, v11, v45
	v_add_f32_e32 v10, v10, v46
	v_add_f32_e32 v11, v11, v47
	v_add_f32_e32 v10, v10, v48
	v_add_f32_e32 v11, v11, v49
	v_add_f32_e32 v10, v10, v50
	v_add_f32_e32 v11, v11, v51
	v_add_f32_e32 v10, v10, v52
	v_add_f32_e32 v11, v11, v53
	v_add_f32_e32 v10, v10, v54
	v_add_f32_e32 v11, v11, v55
	v_add_f32_e32 v10, v10, v56
	v_add_f32_e32 v11, v11, v57
	v_add_f32_e32 v10, v10, v58
	v_add_f32_e32 v11, v11, v59
	v_add_f32_e32 v10, v10, v60
	v_add_f32_e32 v11, v11, v61
	v_add_f32_e32 v10, v10, v62
	v_add_f32_e32 v11, v11, v63
	v_add_f32_e32 v10, v10, v64
	v_add_f32_e32 v11, v11, v65
	v_add_f32_e32 v10, v10, v66
	v_add_f32_e32 v11, v11, v67
	v_add_f32_e32 v10, v10, v68
	v_add_f32_e32 v11, v11, v69
	v_add_f32_e32 v10, v10, v70
	v_add_f32_e32 v11, v11, v71
	v_add_f32_e32 v10, v10, v72
	v_add_f32_e32 v11, v11, v73
	v_lshlrev_b32_e32 v6, 15, v1
	v_add_lshl_u32 v6, v6, v2, 2
	s_add_u32 s6, s20, 0x18000000
	s_addc_u32 s7, s21, 0
	s_add_u32 s8, s20, 0x18005000
	s_addc_u32 s9, s21, 0
	global_store_dword v6, v10, s[6:7]
	global_store_dword v6, v11, s[8:9]

.LBB0_436:
	v_readfirstlane_b32 s0, v223
	s_ashr_i32 s0, s0, 6
	v_readlane_b32 s1, v253, 22
	s_add_i32 s4, s0, s1
	s_cmp_gt_i32 s4, 0x177ff
	s_cbranch_scc1 .LBB0_459
	v_bfe_u32 v0, v223, 5, 1
	v_lshlrev_b32_e32 v5, 3, v223
	s_lshl_b32 s0, s0, 14
	v_and_b32_e32 v1, 31, v223
	s_waitcnt lgkmcnt(0)
	v_bfe_u32 v3, v223, 3, 3
	v_and_b32_e32 v6, 56, v5
	v_mul_u32_u24_e32 v8, 0x2c00, v0
	v_mul_u32_u24_e32 v9, 0x1400, v0
	s_add_i32 s0, s0, 0
	v_mul_u32_u24_e32 v5, 0x84, v6
	v_lshlrev_b32_e32 v7, 2, v3
	v_or_b32_e32 v8, v8, v1
	v_or_b32_e32 v10, v9, v1
	v_lshl_or_b32 v2, v0, 11, v1
	v_lshl_add_u32 v4, v1, 2, s0
	v_add3_u32 v5, s0, v5, v7
	v_or_b32_e32 v7, 8, v3
	v_or_b32_e32 v12, 16, v3
	v_or_b32_e32 v13, 24, v3
	v_mov_b32_e32 v1, v0
	v_lshlrev_b32_e32 v8, 2, v8
	v_lshlrev_b32_e32 v84, 2, v10
	v_readlane_b32 s36, v252, 2
	v_readlane_b32 s37, v252, 3
	s_nop 3
	s_sub_u32 s36, s36, 0xd0
	s_subb_u32 s37, s37, 0
	s_load_dwordx4 s[40:43], s[36:37], 0x78
	v_lshlrev_b32_e32 v90, 2, v6
	s_waitcnt lgkmcnt(0)
	v_mov_b32_e32 v86, s40
	v_mov_b32_e32 v87, s41
	v_mov_b32_e32 v88, s42
	v_mov_b32_e32 v89, s43
	v_add_co_u32_e32 v86, vcc, v90, v86
	s_nop 1
	v_addc_co_u32_e32 v87, vcc, 0, v87, vcc
	v_add_co_u32_e32 v88, vcc, v90, v88
	s_nop 1
	v_addc_co_u32_e32 v89, vcc, 0, v89, vcc
	s_load_dwordx4 s[44:47], s[36:37], 0xa8
	s_waitcnt lgkmcnt(0)
	v_mov_b32_e32 v128, s44
	v_mov_b32_e32 v129, s45
	v_mov_b32_e32 v130, s46
	v_mov_b32_e32 v131, s47
	v_add_co_u32_e32 v128, vcc, v90, v128
	s_nop 1
	v_addc_co_u32_e32 v129, vcc, 0, v129, vcc
	v_add_co_u32_e32 v130, vcc, v90, v130
	s_nop 1
	v_addc_co_u32_e32 v131, vcc, 0, v131, vcc
	s_branch .LBB0_439

.LBB0_456:
	s_mov_b32 s101, s0
	v_readlane_b32 s36, v254, 11
	s_mul_i32 s6, s0, 0x2800000
	v_readlane_b32 s38, v254, 13
	s_mul_hi_i32 s1, s0, 0x2800000
	v_readlane_b32 s39, v254, 14
	s_add_u32 s6, s38, s6
	s_mul_i32 s7, s5, 0x6667
	s_addc_u32 s1, s39, s1
	s_lshr_b32 s8, s7, 31
	s_ashr_i32 s7, s7, 22
	s_add_i32 s7, s7, s8
	s_mul_i32 s8, s7, 0xa0
	s_sub_i32 s5, s5, s8
	s_sext_i32_i16 s5, s5
	s_lshl_b32 s34, s7, 6
	s_lshl_b32 s30, s5, 5
	s_ashr_i32 s35, s34, 31
	s_mul_i32 s7, s7, 0x140000
	s_mul_hi_i32 s5, s34, 0x5000
	s_add_u32 s8, s6, s7
	s_addc_u32 s1, s1, s5
	s_ashr_i32 s31, s30, 31
	s_lshl_b64 s[6:7], s[30:31], 2
	s_add_u32 s6, s8, s6
	s_addc_u32 s7, s1, s7
	v_lshl_add_u64 v[10:11], s[6:7], 0, v[84:85]
	s_mov_b32 s1, 1
	s_mov_b32 s5, 0
	s_mov_b32 s6, 32
	v_readlane_b32 s37, v254, 12
	v_readlane_b32 s40, v254, 15
	v_readlane_b32 s41, v254, 16
	v_readlane_b32 s42, v254, 17
	v_readlane_b32 s43, v254, 18
	v_readlane_b32 s44, v254, 19
	v_readlane_b32 s45, v254, 20
	v_readlane_b32 s46, v254, 21
	v_readlane_b32 s47, v254, 22
	v_readlane_b32 s48, v254, 23
	v_readlane_b32 s49, v254, 24
	v_readlane_b32 s50, v254, 25
	v_readlane_b32 s51, v254, 26
	s_sub_i32 s100, s101, 1
	s_max_i32 s100, s100, 0
	s_lshl_b32 s100, s100, 11
	s_add_i32 s100, s100, s34
	s_lshl_b32 s100, s100, 2
	v_add_co_u32_e32 v90, vcc, s100, v128
	s_nop 1
	v_addc_co_u32_e32 v91, vcc, 0, v129, vcc
	v_add_co_u32_e32 v92, vcc, s100, v130
	s_nop 1
	v_addc_co_u32_e32 v93, vcc, 0, v131, vcc
	global_load_dwordx4 v[94:97], v[90:91], off
	global_load_dwordx4 v[98:101], v[90:91], off offset:16
	global_load_dwordx4 v[102:105], v[92:93], off
	global_load_dwordx4 v[106:109], v[92:93], off offset:16
.LBB0_457:
	s_mul_i32 s36, s1, 0x2800
	s_mul_i32 s28, s5, 0x2800
	s_mov_b32 s37, s29
	s_mov_b32 s39, s29
	s_mov_b32 s41, s29
	s_mov_b32 s43, s29
	s_mov_b32 s45, s29
	s_mov_b32 s47, s29
	s_mov_b32 s49, s29
	s_mov_b32 s11, s29
	s_mov_b32 s13, s29
	s_mov_b32 s15, s29
	s_mov_b32 s17, s29
	s_mov_b32 s51, s29
	s_mov_b32 s53, s29
	s_mov_b32 s55, s29
	v_lshl_add_u64 v[14:15], s[28:29], 2, v[10:11]
	s_add_i32 s40, s36, 0x5000
	s_add_i32 s38, s28, 0x5000
	s_add_i32 s44, s36, 0xa000
	s_add_i32 s42, s28, 0xa000
	s_add_i32 s48, s36, 0xf000
	s_add_i32 s46, s28, 0xf000
	s_add_i32 s12, s36, 0x14000
	s_add_i32 s10, s28, 0x14000
	s_add_i32 s16, s36, 0x19000
	s_add_i32 s14, s28, 0x19000
	s_add_i32 s52, s36, 0x1e000
	s_add_i32 s50, s28, 0x1e000
	s_add_i32 s54, s36, 0x23000
	s_add_i32 s28, s28, 0x23000
	v_lshl_add_u64 v[16:17], s[36:37], 2, v[10:11]
	v_lshl_add_u64 v[18:19], s[38:39], 2, v[10:11]
	v_lshl_add_u64 v[20:21], s[40:41], 2, v[10:11]
	v_lshl_add_u64 v[22:23], s[42:43], 2, v[10:11]
	v_lshl_add_u64 v[24:25], s[44:45], 2, v[10:11]
	v_lshl_add_u64 v[26:27], s[46:47], 2, v[10:11]
	v_lshl_add_u64 v[28:29], s[48:49], 2, v[10:11]
	v_lshl_add_u64 v[30:31], s[10:11], 2, v[10:11]
	v_lshl_add_u64 v[32:33], s[12:13], 2, v[10:11]
	v_lshl_add_u64 v[34:35], s[14:15], 2, v[10:11]
	v_lshl_add_u64 v[36:37], s[16:17], 2, v[10:11]
	v_lshl_add_u64 v[38:39], s[50:51], 2, v[10:11]
	v_lshl_add_u64 v[40:41], s[52:53], 2, v[10:11]
	v_lshl_add_u64 v[42:43], s[28:29], 2, v[10:11]
	v_lshl_add_u64 v[44:45], s[54:55], 2, v[10:11]
	global_load_dword v9, v[14:15], off
	global_load_dword v46, v[16:17], off
	global_load_dword v47, v[18:19], off
	global_load_dword v48, v[20:21], off
	global_load_dword v49, v[22:23], off
	global_load_dword v50, v[24:25], off
	global_load_dword v51, v[26:27], off
	global_load_dword v52, v[28:29], off
	global_load_dword v53, v[30:31], off
	global_load_dword v54, v[32:33], off
	global_load_dword v55, v[34:35], off
	global_load_dword v56, v[36:37], off
	global_load_dword v57, v[38:39], off
	global_load_dword v58, v[40:41], off
	global_load_dword v59, v[42:43], off
	global_load_dword v60, v[44:45], off
	s_lshl_b32 s7, s1, 1
	s_lshl_b32 s8, s5, 1
	v_or_b32_e32 v16, s7, v1
	v_or_b32_e32 v14, s8, v0
	s_add_i32 s5, s5, 16
	s_add_i32 s1, s1, 16
	s_add_i32 s6, s6, -16
	s_add_i32 s10, s7, 4
	s_add_i32 s11, s8, 4
	s_add_i32 s12, s7, 8
	s_add_i32 s13, s8, 8
	s_add_i32 s14, s7, 12
	s_add_i32 s15, s8, 12
	s_add_i32 s16, s7, 16
	s_add_i32 s17, s8, 16
	s_add_i32 s28, s7, 20
	s_add_i32 s31, s8, 20
	s_add_i32 s36, s7, 24
	s_add_i32 s37, s8, 24
	s_add_i32 s7, s7, 28
	s_add_i32 s38, s8, 28
	v_mad_u64_u32 v[14:15], s[8:9], v14, s27, v[4:5]
	v_mad_u64_u32 v[16:17], s[8:9], v16, s27, v[4:5]
	v_or_b32_e32 v15, s10, v1
	v_or_b32_e32 v17, s11, v0
	v_or_b32_e32 v24, s12, v1
	v_or_b32_e32 v22, s13, v0
	v_or_b32_e32 v28, s14, v1
	v_or_b32_e32 v26, s15, v0
	v_or_b32_e32 v32, s16, v1
	v_or_b32_e32 v30, s17, v0
	v_or_b32_e32 v36, s28, v1
	v_or_b32_e32 v34, s31, v0
	v_or_b32_e32 v40, s36, v1
	v_or_b32_e32 v38, s37, v0
	v_or_b32_e32 v44, s7, v1
	v_or_b32_e32 v42, s38, v0
	s_cmp_lg_u32 s6, 0
	v_mad_u64_u32 v[18:19], s[8:9], v17, s27, v[4:5]
	v_mad_u64_u32 v[20:21], s[8:9], v15, s27, v[4:5]
	v_mad_u64_u32 v[22:23], s[8:9], v22, s27, v[4:5]
	v_mad_u64_u32 v[24:25], s[8:9], v24, s27, v[4:5]
	v_mad_u64_u32 v[26:27], s[8:9], v26, s27, v[4:5]
	v_mad_u64_u32 v[28:29], s[8:9], v28, s27, v[4:5]
	v_mad_u64_u32 v[30:31], s[8:9], v30, s27, v[4:5]
	v_mad_u64_u32 v[32:33], s[8:9], v32, s27, v[4:5]
	v_mad_u64_u32 v[34:35], s[8:9], v34, s27, v[4:5]
	v_mad_u64_u32 v[36:37], s[8:9], v36, s27, v[4:5]
	v_mad_u64_u32 v[38:39], s[8:9], v38, s27, v[4:5]
	v_mad_u64_u32 v[40:41], s[8:9], v40, s27, v[4:5]
	v_mad_u64_u32 v[42:43], s[8:9], v42, s27, v[4:5]
	v_mad_u64_u32 v[44:45], s[8:9], v44, s27, v[4:5]
	s_waitcnt vmcnt(0)
	ds_write_b32 v14, v9
	ds_write_b32 v16, v46
	ds_write_b32 v18, v47
	ds_write_b32 v20, v48
	ds_write_b32 v22, v49
	ds_write_b32 v24, v50
	ds_write_b32 v26, v51
	ds_write_b32 v28, v52
	ds_write_b32 v30, v53
	ds_write_b32 v32, v54
	ds_write_b32 v34, v55
	ds_write_b32 v36, v56
	ds_write_b32 v38, v57
	ds_write_b32 v40, v58
	ds_write_b32 v42, v59
	ds_write_b32 v44, v60
	s_cbranch_scc1 .LBB0_457
	s_mul_hi_i32 s1, s0, 0x1400000
	s_mul_i32 s0, s0, 0x1400000
	v_readlane_b32 s5, v253, 48
	s_waitcnt lgkmcnt(0)
	s_add_u32 s5, s5, s0
	v_readlane_b32 s0, v253, 49
	ds_read2_b32 v[18:19], v5 offset0:33 offset1:41
	ds_read2_b32 v[20:21], v5 offset1:8
	ds_read2_b32 v[22:23], v5 offset0:66 offset1:74
	ds_read2_b32 v[24:25], v5 offset0:99 offset1:107
	ds_read2_b32 v[26:27], v5 offset0:132 offset1:140
	ds_read2_b32 v[28:29], v5 offset0:165 offset1:173
	ds_read2_b32 v[30:31], v5 offset0:198 offset1:206
	ds_read2_b32 v[32:33], v5 offset0:231 offset1:239
	s_addc_u32 s6, s0, s1
	s_lshl_b64 s[0:1], s[34:35], 1
	s_add_u32 s0, s5, s0
	v_or_b32_e32 v34, s30, v3
	s_addc_u32 s1, s6, s1
	v_lshlrev_b32_e32 v10, 1, v6
	v_mov_b32_e32 v11, v85
	v_ashrrev_i32_e32 v35, 31, v34
	v_lshl_add_u64 v[10:11], s[0:1], 0, v[10:11]
	v_lshlrev_b64 v[34:35], 12, v[34:35]
	s_waitcnt lgkmcnt(6)
	v_cvt_pk_bf16_f32 v14, v20, v18
	s_waitcnt lgkmcnt(4)
	v_cvt_pk_bf16_f32 v15, v22, v24
	s_waitcnt lgkmcnt(2)
	v_cvt_pk_bf16_f32 v16, v26, v28
	s_waitcnt lgkmcnt(0)
	v_cvt_pk_bf16_f32 v17, v30, v32
	v_lshl_add_u64 v[34:35], v[10:11], 0, v[34:35]
	v_or_b32_e32 v18, s30, v7
	global_store_dwordx4 v[34:35], v[14:17], off
	v_lshlrev_b32_e32 v110, 16, v14
	v_and_b32_e32 v111, 0xffff0000, v14
	v_lshlrev_b32_e32 v112, 16, v15
	v_and_b32_e32 v113, 0xffff0000, v15
	v_lshlrev_b32_e32 v114, 16, v16
	v_and_b32_e32 v115, 0xffff0000, v16
	v_lshlrev_b32_e32 v116, 16, v17
	v_and_b32_e32 v117, 0xffff0000, v17
	v_mul_f32_e32 v118, v94, v110
	v_mul_f32_e32 v119, v102, v110
	v_fmac_f32_e32 v118, v95, v111
	v_fmac_f32_e32 v119, v103, v111
	v_fmac_f32_e32 v118, v96, v112
	v_fmac_f32_e32 v119, v104, v112
	v_fmac_f32_e32 v118, v97, v113
	v_fmac_f32_e32 v119, v105, v113
	v_fmac_f32_e32 v118, v98, v114
	v_fmac_f32_e32 v119, v106, v114
	v_fmac_f32_e32 v118, v99, v115
	v_fmac_f32_e32 v119, v107, v115
	v_fmac_f32_e32 v118, v100, v116
	v_fmac_f32_e32 v119, v108, v116
	v_fmac_f32_e32 v118, v101, v117
	v_fmac_f32_e32 v119, v109, v117
	v_readlane_b32 s50, v254, 61
	v_readlane_b32 s12, v255, 0
	v_cvt_pk_bf16_f32 v14, v21, v19
	v_ashrrev_i32_e32 v19, 31, v18
	v_cvt_pk_bf16_f32 v15, v23, v25
	v_cvt_pk_bf16_f32 v16, v27, v29
	v_cvt_pk_bf16_f32 v17, v31, v33
	v_lshlrev_b64 v[18:19], 12, v[18:19]
	ds_read2_b32 v[20:21], v5 offset0:49 offset1:57
	ds_read2_b32 v[22:23], v5 offset0:16 offset1:24
	ds_read2_b32 v[24:25], v5 offset0:82 offset1:90
	ds_read2_b32 v[26:27], v5 offset0:115 offset1:123
	ds_read2_b32 v[28:29], v5 offset0:148 offset1:156
	ds_read2_b32 v[30:31], v5 offset0:181 offset1:189
	ds_read2_b32 v[32:33], v5 offset0:214 offset1:222
	ds_read2_b32 v[34:35], v5 offset0:247 offset1:255
	v_lshl_add_u64 v[18:19], v[10:11], 0, v[18:19]
	global_store_dwordx4 v[18:19], v[14:17], off
	v_lshlrev_b32_e32 v110, 16, v14
	v_and_b32_e32 v111, 0xffff0000, v14
	v_lshlrev_b32_e32 v112, 16, v15
	v_and_b32_e32 v113, 0xffff0000, v15
	v_lshlrev_b32_e32 v114, 16, v16
	v_and_b32_e32 v115, 0xffff0000, v16
	v_lshlrev_b32_e32 v116, 16, v17
	v_and_b32_e32 v117, 0xffff0000, v17
	v_mul_f32_e32 v120, v94, v110
	v_mul_f32_e32 v121, v102, v110
	v_fmac_f32_e32 v120, v95, v111
	v_fmac_f32_e32 v121, v103, v111
	v_fmac_f32_e32 v120, v96, v112
	v_fmac_f32_e32 v121, v104, v112
	v_fmac_f32_e32 v120, v97, v113
	v_fmac_f32_e32 v121, v105, v113
	v_fmac_f32_e32 v120, v98, v114
	v_fmac_f32_e32 v121, v106, v114
	v_fmac_f32_e32 v120, v99, v115
	v_fmac_f32_e32 v121, v107, v115
	v_fmac_f32_e32 v120, v100, v116
	v_fmac_f32_e32 v121, v108, v116
	v_fmac_f32_e32 v120, v101, v117
	v_fmac_f32_e32 v121, v109, v117
	v_or_b32_e32 v18, s30, v12
	v_ashrrev_i32_e32 v19, 31, v18
	v_lshlrev_b64 v[18:19], 12, v[18:19]
	s_waitcnt lgkmcnt(6)
	v_cvt_pk_bf16_f32 v14, v22, v20
	s_waitcnt lgkmcnt(4)
	v_cvt_pk_bf16_f32 v15, v24, v26
	s_waitcnt lgkmcnt(2)
	v_cvt_pk_bf16_f32 v16, v28, v30
	s_waitcnt lgkmcnt(0)
	v_cvt_pk_bf16_f32 v17, v32, v34
	v_lshl_add_u64 v[18:19], v[10:11], 0, v[18:19]
	global_store_dwordx4 v[18:19], v[14:17], off
	v_lshlrev_b32_e32 v110, 16, v14
	v_and_b32_e32 v111, 0xffff0000, v14
	v_lshlrev_b32_e32 v112, 16, v15
	v_and_b32_e32 v113, 0xffff0000, v15
	v_lshlrev_b32_e32 v114, 16, v16
	v_and_b32_e32 v115, 0xffff0000, v16
	v_lshlrev_b32_e32 v116, 16, v17
	v_and_b32_e32 v117, 0xffff0000, v17
	v_mul_f32_e32 v122, v94, v110
	v_mul_f32_e32 v123, v102, v110
	v_fmac_f32_e32 v122, v95, v111
	v_fmac_f32_e32 v123, v103, v111
	v_fmac_f32_e32 v122, v96, v112
	v_fmac_f32_e32 v123, v104, v112
	v_fmac_f32_e32 v122, v97, v113
	v_fmac_f32_e32 v123, v105, v113
	v_fmac_f32_e32 v122, v98, v114
	v_fmac_f32_e32 v123, v106, v114
	v_fmac_f32_e32 v122, v99, v115
	v_fmac_f32_e32 v123, v107, v115
	v_fmac_f32_e32 v122, v100, v116
	v_fmac_f32_e32 v123, v108, v116
	v_fmac_f32_e32 v122, v101, v117
	v_fmac_f32_e32 v123, v109, v117
	v_or_b32_e32 v18, s30, v13
	v_ashrrev_i32_e32 v19, 31, v18
	v_lshlrev_b64 v[18:19], 12, v[18:19]
	v_cvt_pk_bf16_f32 v14, v23, v21
	v_cvt_pk_bf16_f32 v15, v25, v27
	v_cvt_pk_bf16_f32 v16, v29, v31
	v_cvt_pk_bf16_f32 v17, v33, v35
	v_lshl_add_u64 v[10:11], v[10:11], 0, v[18:19]
	global_store_dwordx4 v[10:11], v[14:17], off
	v_lshlrev_b32_e32 v110, 16, v14
	v_and_b32_e32 v111, 0xffff0000, v14
	v_lshlrev_b32_e32 v112, 16, v15
	v_and_b32_e32 v113, 0xffff0000, v15
	v_lshlrev_b32_e32 v114, 16, v16
	v_and_b32_e32 v115, 0xffff0000, v16
	v_lshlrev_b32_e32 v116, 16, v17
	v_and_b32_e32 v117, 0xffff0000, v17
	v_mul_f32_e32 v124, v94, v110
	v_mul_f32_e32 v125, v102, v110
	v_fmac_f32_e32 v124, v95, v111
	v_fmac_f32_e32 v125, v103, v111
	v_fmac_f32_e32 v124, v96, v112
	v_fmac_f32_e32 v125, v104, v112
	v_fmac_f32_e32 v124, v97, v113
	v_fmac_f32_e32 v125, v105, v113
	v_fmac_f32_e32 v124, v98, v114
	v_fmac_f32_e32 v125, v106, v114
	v_fmac_f32_e32 v124, v99, v115
	v_fmac_f32_e32 v125, v107, v115
	v_fmac_f32_e32 v124, v100, v116
	v_fmac_f32_e32 v125, v108, v116
	v_fmac_f32_e32 v124, v101, v117
	v_fmac_f32_e32 v125, v109, v117
	v_add_f32_dpp v118, v118, v118 quad_perm:[1,0,3,2] row_mask:0xf bank_mask:0xf
	v_add_f32_dpp v119, v119, v119 quad_perm:[1,0,3,2] row_mask:0xf bank_mask:0xf
	v_add_f32_dpp v120, v120, v120 quad_perm:[1,0,3,2] row_mask:0xf bank_mask:0xf
	v_add_f32_dpp v121, v121, v121 quad_perm:[1,0,3,2] row_mask:0xf bank_mask:0xf
	v_add_f32_dpp v122, v122, v122 quad_perm:[1,0,3,2] row_mask:0xf bank_mask:0xf
	v_add_f32_dpp v123, v123, v123 quad_perm:[1,0,3,2] row_mask:0xf bank_mask:0xf
	v_add_f32_dpp v124, v124, v124 quad_perm:[1,0,3,2] row_mask:0xf bank_mask:0xf
	v_add_f32_dpp v125, v125, v125 quad_perm:[1,0,3,2] row_mask:0xf bank_mask:0xf
	v_add_f32_dpp v118, v118, v118 quad_perm:[2,3,0,1] row_mask:0xf bank_mask:0xf
	v_add_f32_dpp v119, v119, v119 quad_perm:[2,3,0,1] row_mask:0xf bank_mask:0xf
	v_add_f32_dpp v120, v120, v120 quad_perm:[2,3,0,1] row_mask:0xf bank_mask:0xf
	v_add_f32_dpp v121, v121, v121 quad_perm:[2,3,0,1] row_mask:0xf bank_mask:0xf
	v_add_f32_dpp v122, v122, v122 quad_perm:[2,3,0,1] row_mask:0xf bank_mask:0xf
	v_add_f32_dpp v123, v123, v123 quad_perm:[2,3,0,1] row_mask:0xf bank_mask:0xf
	v_add_f32_dpp v124, v124, v124 quad_perm:[2,3,0,1] row_mask:0xf bank_mask:0xf
	v_add_f32_dpp v125, v125, v125 quad_perm:[2,3,0,1] row_mask:0xf bank_mask:0xf
	v_add_f32_dpp v118, v118, v118 row_half_mirror row_mask:0xf bank_mask:0xf
	v_add_f32_dpp v119, v119, v119 row_half_mirror row_mask:0xf bank_mask:0xf
	v_add_f32_dpp v120, v120, v120 row_half_mirror row_mask:0xf bank_mask:0xf
	v_add_f32_dpp v121, v121, v121 row_half_mirror row_mask:0xf bank_mask:0xf
	v_add_f32_dpp v122, v122, v122 row_half_mirror row_mask:0xf bank_mask:0xf
	v_add_f32_dpp v123, v123, v123 row_half_mirror row_mask:0xf bank_mask:0xf
	v_add_f32_dpp v124, v124, v124 row_half_mirror row_mask:0xf bank_mask:0xf
	v_add_f32_dpp v125, v125, v125 row_half_mirror row_mask:0xf bank_mask:0xf
	v_cmp_eq_u32_e32 vcc, 0, v6
	s_and_saveexec_b64 s[36:37], vcc
	s_lshl_b32 s100, s101, 5
	s_lshr_b32 s38, s34, 6
	s_add_i32 s100, s100, s38
	s_mul_i32 s100, s100, 0x1400
	s_add_i32 s100, s100, s30
	s_lshl_b32 s100, s100, 3
	s_add_u32 s38, s20, 0x1ac00000
	s_addc_u32 s39, s21, 0
	v_lshlrev_b32_e32 v126, 3, v3
	v_add_u32_e32 v126, s100, v126
	global_store_dwordx2 v126, v[118:119], s[38:39]
	global_store_dwordx2 v126, v[120:121], s[38:39] offset:64
	global_store_dwordx2 v126, v[122:123], s[38:39] offset:128
	global_store_dwordx2 v126, v[124:125], s[38:39] offset:192
	s_or_b64 exec, exec, s[36:37]
	s_waitcnt lgkmcnt(0)
	s_movk_i32 s17, 0x1000
	v_readlane_b32 s51, v254, 62
	v_readlane_b32 s13, v255, 1
	s_branch .LBB0_438
